# static s_setprio 1 for wave half 0 across each GEMM K-loop (the other half stays at 0), no per-block raises
# baseline (speedup 1.0000x reference)
;     __host__ __device__ bool next(int i, Unit& u) const { const long L = (long)i * G + c; if (L >= nwg) return false; return unit_of((int)L, u); }
;     __host__ __device__ bool next(int i, Unit& u) const { const int L = i == 0 ? l0 : (i == 1 ? l1 : (i == 2 ? l2 : -1)); if (L < 0 || L >= s.nwg) return false; return s.unit_of(L, u); }
;     __host__ __device__ bool next(int i, Unit& u) const { const bool ok = s.next(i >> 1, u); u.kh = i & 1; return ok; }
; template <class Epi, class Sched, bool ALIGN_EPI = false, bool SP2 = false>
; __device__ __forceinline__ void gemm_phase(PG8_LAS unsigned char* lds, const Gemm g, const Sched& S, const Epi& E) {
;     ...
;         const bool has_next = S.next(ui + 1, nxt);
;         const char* nA = has_next ? (const char*)g.A + (size_t)nxt.pm * tstep + nxt.kh * khb : cA; const char* nB = has_next ? (const char*)g.Bt + (size_t)nxt.pn * tstep + nxt.kh * khb : cB;
;     ...
;         for (int a = 0; a < 2; ++a)
; #pragma unroll
;             for (int b = 0; b < 2; ++b)
; #pragma unroll
;                 for (int m = 0; m < 4; ++m)
; #pragma unroll
;                     for (int n = 0; n < 2; ++n) acc[a][b][m][n] = (f32x4){0.f, 0.f, 0.f, 0.f};
;         cur = nxt; cA = nA; cB = nB; ++ui;
.LBB0_95:
	s_waitcnt lgkmcnt(0)
	s_ashr_i32 s55, s54, 31
	s_lshl_b64 s[34:35], s[54:55], 19
	s_add_u32 s76, s50, s34
	s_addc_u32 s77, s51, s35
	s_and_b64 s[34:35], s[2:3], exec
	s_cselect_b32 s8, s77, s81
	s_cselect_b32 s55, s76, s80
	s_ashr_i32 s49, s48, 31
	s_lshl_b64 s[34:35], s[48:49], 19
	s_add_u32 s78, s88, s34
	s_addc_u32 s79, s89, s35
	s_and_b64 s[34:35], s[2:3], exec
	s_cselect_b32 s49, s79, s83
	s_cselect_b32 vcc_lo, s78, s82
	s_add_u32 s80, s80, 0x40080
	s_addc_u32 s81, s81, 0
	s_add_u32 vcc_hi, s82, 0x100
	v_mov_b32_e32 v0, 0
	s_addc_u32 s34, s83, 0
	s_mov_b32 s35, -2
	v_mov_b32_e32 v1, v0
	v_mov_b32_e32 v2, v0
	v_mov_b32_e32 v3, v0
	v_mov_b32_e32 v4, v0
	v_mov_b32_e32 v5, v0
	v_mov_b32_e32 v6, v0
	v_mov_b32_e32 v7, v0
	v_mov_b32_e32 v16, v0
	v_mov_b32_e32 v17, v0
	v_mov_b32_e32 v18, v0
	v_mov_b32_e32 v19, v0
	v_mov_b32_e32 v20, v0
	v_mov_b32_e32 v21, v0
	v_mov_b32_e32 v22, v0
	v_mov_b32_e32 v23, v0
	v_mov_b32_e32 v32, v0
	v_mov_b32_e32 v33, v0
	v_mov_b32_e32 v34, v0
	v_mov_b32_e32 v35, v0
	v_mov_b32_e32 v36, v0
	v_mov_b32_e32 v37, v0
	v_mov_b32_e32 v38, v0
	v_mov_b32_e32 v39, v0
	v_mov_b32_e32 v48, v0
	v_mov_b32_e32 v49, v0
	v_mov_b32_e32 v50, v0
	v_mov_b32_e32 v51, v0
	v_mov_b32_e32 v52, v0
	v_mov_b32_e32 v53, v0
	v_mov_b32_e32 v54, v0
	v_mov_b32_e32 v55, v0
	v_mov_b32_e32 v8, v0
	v_mov_b32_e32 v9, v0
	v_mov_b32_e32 v10, v0
	v_mov_b32_e32 v11, v0
	v_mov_b32_e32 v12, v0
	v_mov_b32_e32 v13, v0
	v_mov_b32_e32 v14, v0
	v_mov_b32_e32 v15, v0
	v_mov_b32_e32 v24, v0
	v_mov_b32_e32 v25, v0
	v_mov_b32_e32 v26, v0
	v_mov_b32_e32 v27, v0
	v_mov_b32_e32 v28, v0
	v_mov_b32_e32 v29, v0
	v_mov_b32_e32 v30, v0
	v_mov_b32_e32 v31, v0
	v_mov_b32_e32 v40, v0
	v_mov_b32_e32 v41, v0
	v_mov_b32_e32 v42, v0
	v_mov_b32_e32 v43, v0
	v_mov_b32_e32 v44, v0
	v_mov_b32_e32 v45, v0
	v_mov_b32_e32 v46, v0
	v_mov_b32_e32 v47, v0
	v_mov_b32_e32 v56, v0
	v_mov_b32_e32 v57, v0
	v_mov_b32_e32 v58, v0
	v_mov_b32_e32 v59, v0
	v_mov_b32_e32 v60, v0
	v_mov_b32_e32 v61, v0
	v_mov_b32_e32 v62, v0
	v_mov_b32_e32 v63, v0
	v_mov_b32_e32 v64, v0
	v_mov_b32_e32 v65, v0
	v_mov_b32_e32 v66, v0
	v_mov_b32_e32 v67, v0
	v_mov_b32_e32 v68, v0
	v_mov_b32_e32 v69, v0
	v_mov_b32_e32 v70, v0
	v_mov_b32_e32 v71, v0
	v_mov_b32_e32 v80, v0
	v_mov_b32_e32 v81, v0
	v_mov_b32_e32 v82, v0
	v_mov_b32_e32 v83, v0
	v_mov_b32_e32 v84, v0
	v_mov_b32_e32 v85, v0
	v_mov_b32_e32 v86, v0
	v_mov_b32_e32 v87, v0
	v_mov_b32_e32 v96, v0
	v_mov_b32_e32 v97, v0
	v_mov_b32_e32 v98, v0
	v_mov_b32_e32 v99, v0
	v_mov_b32_e32 v100, v0
	v_mov_b32_e32 v101, v0
	v_mov_b32_e32 v102, v0
	v_mov_b32_e32 v103, v0
	v_mov_b32_e32 v112, v0
	v_mov_b32_e32 v113, v0
	v_mov_b32_e32 v114, v0
	v_mov_b32_e32 v115, v0
	v_mov_b32_e32 v116, v0
	v_mov_b32_e32 v117, v0
	v_mov_b32_e32 v118, v0
	v_mov_b32_e32 v119, v0
	v_mov_b32_e32 v72, v0
	v_mov_b32_e32 v73, v0
	v_mov_b32_e32 v74, v0
	v_mov_b32_e32 v75, v0
	v_mov_b32_e32 v76, v0
	v_mov_b32_e32 v77, v0
	v_mov_b32_e32 v78, v0
	v_mov_b32_e32 v79, v0
	v_mov_b32_e32 v88, v0
	v_mov_b32_e32 v89, v0
	v_mov_b32_e32 v90, v0
	v_mov_b32_e32 v91, v0
	v_mov_b32_e32 v92, v0
	v_mov_b32_e32 v93, v0
	v_mov_b32_e32 v94, v0
	v_mov_b32_e32 v95, v0
	v_mov_b32_e32 v104, v0
	v_mov_b32_e32 v105, v0
	v_mov_b32_e32 v106, v0
	v_mov_b32_e32 v107, v0
	v_mov_b32_e32 v108, v0
	v_mov_b32_e32 v109, v0
	v_mov_b32_e32 v110, v0
	v_mov_b32_e32 v111, v0
	v_mov_b32_e32 v120, v0
	v_mov_b32_e32 v121, v0
	v_mov_b32_e32 v122, v0
	v_mov_b32_e32 v123, v0
	v_mov_b32_e32 v124, v0
	v_mov_b32_e32 v125, v0
	v_mov_b32_e32 v126, v0
	v_mov_b32_e32 v127, v0
	v_readfirstlane_b32 s100, v188
	s_bitcmp0_b32 s100, 8
	s_cbranch_scc0 .Lmy_sprio_96
	s_setprio 1

;     __host__ __device__ bool next(int i, Unit& u) const { const long L = (long)i * G + c; if (L >= nwg) return false; return unit_of((int)L, u); }
;     __host__ __device__ bool next(int i, Unit& u) const { const int L = i == 0 ? l0 : (i == 1 ? l1 : (i == 2 ? l2 : -1)); if (L < 0 || L >= s.nwg) return false; return s.unit_of(L, u); }
;     __host__ __device__ bool next(int i, Unit& u) const { const bool ok = s.next(i >> 1, u); u.kh = i & 1; return ok; }
; template <class Epi, class Sched, bool ALIGN_EPI = false, bool SP2 = false>
; __device__ __forceinline__ void gemm_phase(PG8_LAS unsigned char* lds, const Gemm g, const Sched& S, const Epi& E) {
;     ...
;         const bool has_next = S.next(ui + 1, nxt);
;         const char* nA = has_next ? (const char*)g.A + (size_t)nxt.pm * tstep + nxt.kh * khb : cA; const char* nB = has_next ? (const char*)g.Bt + (size_t)nxt.pn * tstep + nxt.kh * khb : cB;
;     ...
;         for (int a = 0; a < 2; ++a)
; #pragma unroll
;             for (int b = 0; b < 2; ++b)
; #pragma unroll
;                 for (int m = 0; m < 4; ++m)
; #pragma unroll
;                     for (int n = 0; n < 2; ++n) acc[a][b][m][n] = (f32x4){0.f, 0.f, 0.f, 0.f};
;         cur = nxt; cA = nA; cB = nB; ++ui;
.LBB0_149:
	s_ashr_i32 s17, s16, 31
	s_lshl_b64 s[18:19], s[16:17], 19
	s_add_u32 s18, s29, s18
	s_addc_u32 s19, s30, s19
	s_and_b64 s[20:21], s[2:3], exec
	s_cselect_b32 s17, s19, s23
	s_cselect_b32 s45, s18, s22
	s_ashr_i32 s15, s14, 31
	s_lshl_b64 s[20:21], s[14:15], 19
	s_add_u32 s20, s50, s20
	s_addc_u32 s21, s51, s21
	s_and_b64 s[26:27], s[2:3], exec
	s_cselect_b32 s15, s21, s25
	s_cselect_b32 s46, s20, s24
	s_add_u32 s22, s22, 0x40080
	s_addc_u32 s23, s23, 0
	s_add_u32 s47, s24, 0x100
	v_mov_b32_e32 v0, 0
	s_addc_u32 s48, s25, 0
	s_mov_b32 s49, -2
	v_mov_b32_e32 v1, v0
	v_mov_b32_e32 v2, v0
	v_mov_b32_e32 v3, v0
	v_mov_b32_e32 v4, v0
	v_mov_b32_e32 v5, v0
	v_mov_b32_e32 v6, v0
	v_mov_b32_e32 v7, v0
	v_mov_b32_e32 v8, v0
	v_mov_b32_e32 v9, v0
	v_mov_b32_e32 v10, v0
	v_mov_b32_e32 v11, v0
	v_mov_b32_e32 v12, v0
	v_mov_b32_e32 v13, v0
	v_mov_b32_e32 v14, v0
	v_mov_b32_e32 v15, v0
	v_mov_b32_e32 v24, v0
	v_mov_b32_e32 v25, v0
	v_mov_b32_e32 v26, v0
	v_mov_b32_e32 v27, v0
	v_mov_b32_e32 v28, v0
	v_mov_b32_e32 v29, v0
	v_mov_b32_e32 v30, v0
	v_mov_b32_e32 v31, v0
	v_mov_b32_e32 v40, v0
	v_mov_b32_e32 v41, v0
	v_mov_b32_e32 v42, v0
	v_mov_b32_e32 v43, v0
	v_mov_b32_e32 v44, v0
	v_mov_b32_e32 v45, v0
	v_mov_b32_e32 v46, v0
	v_mov_b32_e32 v47, v0
	v_mov_b32_e32 v16, v0
	v_mov_b32_e32 v17, v0
	v_mov_b32_e32 v18, v0
	v_mov_b32_e32 v19, v0
	v_mov_b32_e32 v20, v0
	v_mov_b32_e32 v21, v0
	v_mov_b32_e32 v22, v0
	v_mov_b32_e32 v23, v0
	v_mov_b32_e32 v32, v0
	v_mov_b32_e32 v33, v0
	v_mov_b32_e32 v34, v0
	v_mov_b32_e32 v35, v0
	v_mov_b32_e32 v36, v0
	v_mov_b32_e32 v37, v0
	v_mov_b32_e32 v38, v0
	v_mov_b32_e32 v39, v0
	v_mov_b32_e32 v48, v0
	v_mov_b32_e32 v49, v0
	v_mov_b32_e32 v50, v0
	v_mov_b32_e32 v51, v0
	v_mov_b32_e32 v52, v0
	v_mov_b32_e32 v53, v0
	v_mov_b32_e32 v54, v0
	v_mov_b32_e32 v55, v0
	v_mov_b32_e32 v56, v0
	v_mov_b32_e32 v57, v0
	v_mov_b32_e32 v58, v0
	v_mov_b32_e32 v59, v0
	v_mov_b32_e32 v60, v0
	v_mov_b32_e32 v61, v0
	v_mov_b32_e32 v62, v0
	v_mov_b32_e32 v63, v0
	v_mov_b32_e32 v64, v0
	v_mov_b32_e32 v65, v0
	v_mov_b32_e32 v66, v0
	v_mov_b32_e32 v67, v0
	v_mov_b32_e32 v68, v0
	v_mov_b32_e32 v69, v0
	v_mov_b32_e32 v70, v0
	v_mov_b32_e32 v71, v0
	v_mov_b32_e32 v72, v0
	v_mov_b32_e32 v73, v0
	v_mov_b32_e32 v74, v0
	v_mov_b32_e32 v75, v0
	v_mov_b32_e32 v76, v0
	v_mov_b32_e32 v77, v0
	v_mov_b32_e32 v78, v0
	v_mov_b32_e32 v79, v0
	v_mov_b32_e32 v88, v0
	v_mov_b32_e32 v89, v0
	v_mov_b32_e32 v90, v0
	v_mov_b32_e32 v91, v0
	v_mov_b32_e32 v92, v0
	v_mov_b32_e32 v93, v0
	v_mov_b32_e32 v94, v0
	v_mov_b32_e32 v95, v0
	v_mov_b32_e32 v104, v0
	v_mov_b32_e32 v105, v0
	v_mov_b32_e32 v106, v0
	v_mov_b32_e32 v107, v0
	v_mov_b32_e32 v108, v0
	v_mov_b32_e32 v109, v0
	v_mov_b32_e32 v110, v0
	v_mov_b32_e32 v111, v0
	v_mov_b32_e32 v80, v0
	v_mov_b32_e32 v81, v0
	v_mov_b32_e32 v82, v0
	v_mov_b32_e32 v83, v0
	v_mov_b32_e32 v84, v0
	v_mov_b32_e32 v85, v0
	v_mov_b32_e32 v86, v0
	v_mov_b32_e32 v87, v0
	v_mov_b32_e32 v96, v0
	v_mov_b32_e32 v97, v0
	v_mov_b32_e32 v98, v0
	v_mov_b32_e32 v99, v0
	v_mov_b32_e32 v100, v0
	v_mov_b32_e32 v101, v0
	v_mov_b32_e32 v102, v0
	v_mov_b32_e32 v103, v0
	v_mov_b32_e32 v112, v0
	v_mov_b32_e32 v113, v0
	v_mov_b32_e32 v114, v0
	v_mov_b32_e32 v115, v0
	v_mov_b32_e32 v116, v0
	v_mov_b32_e32 v117, v0
	v_mov_b32_e32 v118, v0
	v_mov_b32_e32 v119, v0
	v_mov_b32_e32 v120, v0
	v_mov_b32_e32 v121, v0
	v_mov_b32_e32 v122, v0
	v_mov_b32_e32 v123, v0
	v_mov_b32_e32 v124, v0
	v_mov_b32_e32 v125, v0
	v_mov_b32_e32 v126, v0
	v_mov_b32_e32 v127, v0
	v_readfirstlane_b32 s100, v188
	s_bitcmp0_b32 s100, 8
	s_cbranch_scc0 .Lmy_sprio_150
	s_setprio 1

;     __host__ __device__ bool next(int i, Unit& u) const { const long L = (long)i * G + c; if (L >= nwg) return false; return unit_of((int)L, u); }
;     __host__ __device__ bool next(int i, Unit& u) const { const int L = i == 0 ? l0 : (i == 1 ? l1 : (i == 2 ? l2 : -1)); if (L < 0 || L >= s.nwg) return false; return s.unit_of(L, u); }
;     __host__ __device__ bool next(int i, Unit& u) const { const bool ok = s.next(i >> 1, u); u.kh = i & 1; return ok; }
; template <class Epi, class Sched, bool ALIGN_EPI = false, bool SP2 = false>
; __device__ __forceinline__ void gemm_phase(PG8_LAS unsigned char* lds, const Gemm g, const Sched& S, const Epi& E) {
;     ...
;         const bool has_next = S.next(ui + 1, nxt);
;         const char* nA = has_next ? (const char*)g.A + (size_t)nxt.pm * tstep + nxt.kh * khb : cA; const char* nB = has_next ? (const char*)g.Bt + (size_t)nxt.pn * tstep + nxt.kh * khb : cB;
;     ...
;         for (int a = 0; a < 2; ++a)
; #pragma unroll
;             for (int b = 0; b < 2; ++b)
; #pragma unroll
;                 for (int m = 0; m < 4; ++m)
; #pragma unroll
;                     for (int n = 0; n < 2; ++n) acc[a][b][m][n] = (f32x4){0.f, 0.f, 0.f, 0.f};
;         cur = nxt; cA = nA; cB = nB; ++ui;
.LBB0_683:
	s_ashr_i32 s3, s2, 31
	s_lshl_b64 s[12:13], s[2:3], 19
	v_readlane_b32 s3, v254, 13
	s_add_u32 s16, s3, s12
	v_readlane_b32 s3, v254, 17
	s_addc_u32 s17, s3, s13
	s_and_b64 s[12:13], s[38:39], exec
	s_cselect_b32 s3, s17, s1
	s_cselect_b32 s94, s16, s0
	s_ashr_i32 s5, s4, 31
	s_lshl_b64 s[12:13], s[4:5], 19
	v_readlane_b32 s5, v254, 15
	s_add_u32 s12, s5, s12
	s_addc_u32 s13, s50, s13
	s_and_b64 s[42:43], s[38:39], exec
	s_cselect_b32 s5, s13, s41
	s_cselect_b32 s95, s12, s40
	s_add_u32 s0, s0, 0x40080
	s_addc_u32 s1, s1, 0
	s_add_u32 s96, s40, 0x100
	v_mov_b32_e32 v0, 0
	s_addc_u32 s97, s41, 0
	s_mov_b32 vcc_lo, -2
	v_mov_b32_e32 v1, v0
	v_mov_b32_e32 v2, v0
	v_mov_b32_e32 v3, v0
	v_mov_b32_e32 v4, v0
	v_mov_b32_e32 v5, v0
	v_mov_b32_e32 v6, v0
	v_mov_b32_e32 v7, v0
	v_mov_b32_e32 v16, v0
	v_mov_b32_e32 v17, v0
	v_mov_b32_e32 v18, v0
	v_mov_b32_e32 v19, v0
	v_mov_b32_e32 v20, v0
	v_mov_b32_e32 v21, v0
	v_mov_b32_e32 v22, v0
	v_mov_b32_e32 v23, v0
	v_mov_b32_e32 v32, v0
	v_mov_b32_e32 v33, v0
	v_mov_b32_e32 v34, v0
	v_mov_b32_e32 v35, v0
	v_mov_b32_e32 v36, v0
	v_mov_b32_e32 v37, v0
	v_mov_b32_e32 v38, v0
	v_mov_b32_e32 v39, v0
	v_mov_b32_e32 v48, v0
	v_mov_b32_e32 v49, v0
	v_mov_b32_e32 v50, v0
	v_mov_b32_e32 v51, v0
	v_mov_b32_e32 v52, v0
	v_mov_b32_e32 v53, v0
	v_mov_b32_e32 v54, v0
	v_mov_b32_e32 v55, v0
	v_mov_b32_e32 v8, v0
	v_mov_b32_e32 v9, v0
	v_mov_b32_e32 v10, v0
	v_mov_b32_e32 v11, v0
	v_mov_b32_e32 v12, v0
	v_mov_b32_e32 v13, v0
	v_mov_b32_e32 v14, v0
	v_mov_b32_e32 v15, v0
	v_mov_b32_e32 v24, v0
	v_mov_b32_e32 v25, v0
	v_mov_b32_e32 v26, v0
	v_mov_b32_e32 v27, v0
	v_mov_b32_e32 v28, v0
	v_mov_b32_e32 v29, v0
	v_mov_b32_e32 v30, v0
	v_mov_b32_e32 v31, v0
	v_mov_b32_e32 v40, v0
	v_mov_b32_e32 v41, v0
	v_mov_b32_e32 v42, v0
	v_mov_b32_e32 v43, v0
	v_mov_b32_e32 v44, v0
	v_mov_b32_e32 v45, v0
	v_mov_b32_e32 v46, v0
	v_mov_b32_e32 v47, v0
	v_mov_b32_e32 v56, v0
	v_mov_b32_e32 v57, v0
	v_mov_b32_e32 v58, v0
	v_mov_b32_e32 v59, v0
	v_mov_b32_e32 v60, v0
	v_mov_b32_e32 v61, v0
	v_mov_b32_e32 v62, v0
	v_mov_b32_e32 v63, v0
	v_mov_b32_e32 v64, v0
	v_mov_b32_e32 v65, v0
	v_mov_b32_e32 v66, v0
	v_mov_b32_e32 v67, v0
	v_mov_b32_e32 v68, v0
	v_mov_b32_e32 v69, v0
	v_mov_b32_e32 v70, v0
	v_mov_b32_e32 v71, v0
	v_mov_b32_e32 v80, v0
	v_mov_b32_e32 v81, v0
	v_mov_b32_e32 v82, v0
	v_mov_b32_e32 v83, v0
	v_mov_b32_e32 v84, v0
	v_mov_b32_e32 v85, v0
	v_mov_b32_e32 v86, v0
	v_mov_b32_e32 v87, v0
	v_mov_b32_e32 v96, v0
	v_mov_b32_e32 v97, v0
	v_mov_b32_e32 v98, v0
	v_mov_b32_e32 v99, v0
	v_mov_b32_e32 v100, v0
	v_mov_b32_e32 v101, v0
	v_mov_b32_e32 v102, v0
	v_mov_b32_e32 v103, v0
	v_mov_b32_e32 v112, v0
	v_mov_b32_e32 v113, v0
	v_mov_b32_e32 v114, v0
	v_mov_b32_e32 v115, v0
	v_mov_b32_e32 v116, v0
	v_mov_b32_e32 v117, v0
	v_mov_b32_e32 v118, v0
	v_mov_b32_e32 v119, v0
	v_mov_b32_e32 v72, v0
	v_mov_b32_e32 v73, v0
	v_mov_b32_e32 v74, v0
	v_mov_b32_e32 v75, v0
	v_mov_b32_e32 v76, v0
	v_mov_b32_e32 v77, v0
	v_mov_b32_e32 v78, v0
	v_mov_b32_e32 v79, v0
	v_mov_b32_e32 v88, v0
	v_mov_b32_e32 v89, v0
	v_mov_b32_e32 v90, v0
	v_mov_b32_e32 v91, v0
	v_mov_b32_e32 v92, v0
	v_mov_b32_e32 v93, v0
	v_mov_b32_e32 v94, v0
	v_mov_b32_e32 v95, v0
	v_mov_b32_e32 v104, v0
	v_mov_b32_e32 v105, v0
	v_mov_b32_e32 v106, v0
	v_mov_b32_e32 v107, v0
	v_mov_b32_e32 v108, v0
	v_mov_b32_e32 v109, v0
	v_mov_b32_e32 v110, v0
	v_mov_b32_e32 v111, v0
	v_mov_b32_e32 v120, v0
	v_mov_b32_e32 v121, v0
	v_mov_b32_e32 v122, v0
	v_mov_b32_e32 v123, v0
	v_mov_b32_e32 v124, v0
	v_mov_b32_e32 v125, v0
	v_mov_b32_e32 v126, v0
	v_mov_b32_e32 v127, v0
	v_readfirstlane_b32 s100, v188
	s_bitcmp0_b32 s100, 8
	s_cbranch_scc0 .Lmy_sprio_684
	s_setprio 1

;     __host__ __device__ bool next(int i, Unit& u) const { const long L = (long)i * G + c; if (L >= nwg) return false; return unit_of((int)L, u); }
;     __host__ __device__ bool next(int i, Unit& u) const { const int L = i == 0 ? l0 : (i == 1 ? l1 : (i == 2 ? l2 : -1)); if (L < 0 || L >= s.nwg) return false; return s.unit_of(L, u); }
;     __host__ __device__ bool next(int i, Unit& u) const { const bool ok = s.next(i >> 1, u); u.kh = i & 1; return ok; }
; template <class Epi, class Sched, bool ALIGN_EPI = false, bool SP2 = false>
; __device__ __forceinline__ void gemm_phase(PG8_LAS unsigned char* lds, const Gemm g, const Sched& S, const Epi& E) {
;     ...
;         const bool has_next = S.next(ui + 1, nxt);
;         const char* nA = has_next ? (const char*)g.A + (size_t)nxt.pm * tstep + nxt.kh * khb : cA; const char* nB = has_next ? (const char*)g.Bt + (size_t)nxt.pn * tstep + nxt.kh * khb : cB;
.LBB0_794:
	s_ashr_i32 s41, s40, 31
	s_and_b32 s76, s69, 1
	s_lshl_b64 s[42:43], s[40:41], 20
	s_add_u32 s39, s50, s42
	s_addc_u32 s41, s51, s43
	s_lshl_b32 s56, s76, 11
	s_add_u32 s42, s39, s56
	s_addc_u32 s43, s41, 0
	s_and_b64 s[44:45], s[2:3], exec
	s_cselect_b32 s41, s43, s47
	s_cselect_b32 s78, s42, s46
	s_ashr_i32 s39, s38, 31
	s_lshl_b64 s[44:45], s[38:39], 20
	s_add_u32 s39, s58, s44
	s_addc_u32 s45, s59, s45
	s_add_u32 s44, s39, s56
	s_addc_u32 s45, s45, 0
	s_and_b64 s[56:57], s[2:3], exec
	s_cselect_b32 s39, s45, s55
	s_cselect_b32 s79, s44, s54
	s_add_u32 s46, s46, 0x80080
	s_addc_u32 s47, s47, 0
	s_add_u32 s80, s54, 0x100
	s_addc_u32 s81, s55, 0
	s_mov_b32 s82, -2
	v_readfirstlane_b32 s100, v188
	s_bitcmp0_b32 s100, 8
	s_cbranch_scc0 .Lmy_sprio_795
	s_setprio 1

;     __host__ __device__ bool next(int i, Unit& u) const { const long L = (long)i * G + c; if (L >= nwg) return false; return unit_of((int)L, u); }
;     __host__ __device__ bool next(int i, Unit& u) const { const int L = i == 0 ? l0 : (i == 1 ? l1 : (i == 2 ? l2 : -1)); if (L < 0 || L >= s.nwg) return false; return s.unit_of(L, u); }
;     __host__ __device__ bool next(int i, Unit& u) const { const bool ok = s.next(i >> 1, u); u.kh = i & 1; return ok; }
; template <class Epi, class Sched, bool ALIGN_EPI = false, bool SP2 = false>
; __device__ __forceinline__ void gemm_phase(PG8_LAS unsigned char* lds, const Gemm g, const Sched& S, const Epi& E) {
;     ...
;         const bool has_next = S.next(ui + 1, nxt);
;         const char* nA = has_next ? (const char*)g.A + (size_t)nxt.pm * tstep + nxt.kh * khb : cA; const char* nB = has_next ? (const char*)g.Bt + (size_t)nxt.pn * tstep + nxt.kh * khb : cB;
;     ...
;         for (int a = 0; a < 2; ++a)
; #pragma unroll
;             for (int b = 0; b < 2; ++b)
; #pragma unroll
;                 for (int m = 0; m < 4; ++m)
; #pragma unroll
;                     for (int n = 0; n < 2; ++n) acc[a][b][m][n] = (f32x4){0.f, 0.f, 0.f, 0.f};
;         cur = nxt; cA = nA; cB = nB; ++ui;
.LBB0_881:
	s_ashr_i32 s23, s22, 31
	s_lshl_b64 s[24:25], s[22:23], 19
	s_add_u32 s24, s38, s24
	s_addc_u32 s25, s39, s25
	s_and_b64 s[26:27], s[4:5], exec
	s_cselect_b32 s23, s25, s31
	s_cselect_b32 s29, s24, s30
	s_ashr_i32 s21, s20, 31
	s_lshl_b64 s[26:27], s[20:21], 19
	s_add_u32 s26, s40, s26
	s_addc_u32 s27, s41, s27
	s_and_b64 s[36:37], s[4:5], exec
	s_cselect_b32 s21, s27, s35
	s_cselect_b32 s58, s26, s34
	s_add_u32 s30, s30, 0x40080
	s_addc_u32 s31, s31, 0
	s_add_u32 s59, s34, 0x100
	v_mov_b32_e32 v0, 0
	s_addc_u32 s60, s35, 0
	s_mov_b32 s61, -2
	s_waitcnt lgkmcnt(0)
	v_mov_b32_e32 v1, v0
	v_mov_b32_e32 v2, v0
	v_mov_b32_e32 v3, v0
	v_mov_b32_e32 v4, v0
	v_mov_b32_e32 v5, v0
	v_mov_b32_e32 v6, v0
	v_mov_b32_e32 v7, v0
	v_mov_b32_e32 v16, v0
	v_mov_b32_e32 v17, v0
	v_mov_b32_e32 v18, v0
	v_mov_b32_e32 v19, v0
	v_mov_b32_e32 v20, v0
	v_mov_b32_e32 v21, v0
	v_mov_b32_e32 v22, v0
	v_mov_b32_e32 v23, v0
	v_mov_b32_e32 v32, v0
	v_mov_b32_e32 v33, v0
	v_mov_b32_e32 v34, v0
	v_mov_b32_e32 v35, v0
	v_mov_b32_e32 v36, v0
	v_mov_b32_e32 v37, v0
	v_mov_b32_e32 v38, v0
	v_mov_b32_e32 v39, v0
	v_mov_b32_e32 v48, v0
	v_mov_b32_e32 v49, v0
	v_mov_b32_e32 v50, v0
	v_mov_b32_e32 v51, v0
	v_mov_b32_e32 v52, v0
	v_mov_b32_e32 v53, v0
	v_mov_b32_e32 v54, v0
	v_mov_b32_e32 v55, v0
	v_mov_b32_e32 v8, v0
	v_mov_b32_e32 v9, v0
	v_mov_b32_e32 v10, v0
	v_mov_b32_e32 v11, v0
	v_mov_b32_e32 v12, v0
	v_mov_b32_e32 v13, v0
	v_mov_b32_e32 v14, v0
	v_mov_b32_e32 v15, v0
	v_mov_b32_e32 v24, v0
	v_mov_b32_e32 v25, v0
	v_mov_b32_e32 v26, v0
	v_mov_b32_e32 v27, v0
	v_mov_b32_e32 v28, v0
	v_mov_b32_e32 v29, v0
	v_mov_b32_e32 v30, v0
	v_mov_b32_e32 v31, v0
	v_mov_b32_e32 v40, v0
	v_mov_b32_e32 v41, v0
	v_mov_b32_e32 v42, v0
	v_mov_b32_e32 v43, v0
	v_mov_b32_e32 v44, v0
	v_mov_b32_e32 v45, v0
	v_mov_b32_e32 v46, v0
	v_mov_b32_e32 v47, v0
	v_mov_b32_e32 v56, v0
	v_mov_b32_e32 v57, v0
	v_mov_b32_e32 v58, v0
	v_mov_b32_e32 v59, v0
	v_mov_b32_e32 v60, v0
	v_mov_b32_e32 v61, v0
	v_mov_b32_e32 v62, v0
	v_mov_b32_e32 v63, v0
	v_mov_b32_e32 v64, v0
	v_mov_b32_e32 v65, v0
	v_mov_b32_e32 v66, v0
	v_mov_b32_e32 v67, v0
	v_mov_b32_e32 v68, v0
	v_mov_b32_e32 v69, v0
	v_mov_b32_e32 v70, v0
	v_mov_b32_e32 v71, v0
	v_mov_b32_e32 v80, v0
	v_mov_b32_e32 v81, v0
	v_mov_b32_e32 v82, v0
	v_mov_b32_e32 v83, v0
	v_mov_b32_e32 v84, v0
	v_mov_b32_e32 v85, v0
	v_mov_b32_e32 v86, v0
	v_mov_b32_e32 v87, v0
	v_mov_b32_e32 v96, v0
	v_mov_b32_e32 v97, v0
	v_mov_b32_e32 v98, v0
	v_mov_b32_e32 v99, v0
	v_mov_b32_e32 v100, v0
	v_mov_b32_e32 v101, v0
	v_mov_b32_e32 v102, v0
	v_mov_b32_e32 v103, v0
	v_mov_b32_e32 v112, v0
	v_mov_b32_e32 v113, v0
	v_mov_b32_e32 v114, v0
	v_mov_b32_e32 v115, v0
	v_mov_b32_e32 v116, v0
	v_mov_b32_e32 v117, v0
	v_mov_b32_e32 v118, v0
	v_mov_b32_e32 v119, v0
	v_mov_b32_e32 v72, v0
	v_mov_b32_e32 v73, v0
	v_mov_b32_e32 v74, v0
	v_mov_b32_e32 v75, v0
	v_mov_b32_e32 v76, v0
	v_mov_b32_e32 v77, v0
	v_mov_b32_e32 v78, v0
	v_mov_b32_e32 v79, v0
	v_mov_b32_e32 v88, v0
	v_mov_b32_e32 v89, v0
	v_mov_b32_e32 v90, v0
	v_mov_b32_e32 v91, v0
	v_mov_b32_e32 v92, v0
	v_mov_b32_e32 v93, v0
	v_mov_b32_e32 v94, v0
	v_mov_b32_e32 v95, v0
	v_mov_b32_e32 v104, v0
	v_mov_b32_e32 v105, v0
	v_mov_b32_e32 v106, v0
	v_mov_b32_e32 v107, v0
	v_mov_b32_e32 v108, v0
	v_mov_b32_e32 v109, v0
	v_mov_b32_e32 v110, v0
	v_mov_b32_e32 v111, v0
	v_mov_b32_e32 v120, v0
	v_mov_b32_e32 v121, v0
	v_mov_b32_e32 v122, v0
	v_mov_b32_e32 v123, v0
	v_mov_b32_e32 v124, v0
	v_mov_b32_e32 v125, v0
	v_mov_b32_e32 v126, v0
	v_mov_b32_e32 v127, v0
	v_readfirstlane_b32 s100, v188
	s_bitcmp0_b32 s100, 8
	s_cbranch_scc0 .Lmy_sprio_882
	s_setprio 1

;     __host__ __device__ bool next(int i, Unit& u) const { const long L = (long)i * G + c; if (L >= nwg) return false; return unit_of((int)L, u); }
;     __host__ __device__ bool next(int i, Unit& u) const { const int L = i == 0 ? l0 : (i == 1 ? l1 : (i == 2 ? l2 : -1)); if (L < 0 || L >= s.nwg) return false; return s.unit_of(L, u); }
;     __host__ __device__ bool next(int i, Unit& u) const { const bool ok = s.next(i >> 1, u); u.kh = i & 1; return ok; }
; template <class Epi, class Sched, bool ALIGN_EPI = false, bool SP2 = false>
; __device__ __forceinline__ void gemm_phase(PG8_LAS unsigned char* lds, const Gemm g, const Sched& S, const Epi& E) {
;     ...
;         const bool has_next = S.next(ui + 1, nxt);
;         const char* nA = has_next ? (const char*)g.A + (size_t)nxt.pm * tstep + nxt.kh * khb : cA; const char* nB = has_next ? (const char*)g.Bt + (size_t)nxt.pn * tstep + nxt.kh * khb : cB;
;     ...
;         for (int a = 0; a < 2; ++a)
; #pragma unroll
;             for (int b = 0; b < 2; ++b)
; #pragma unroll
;                 for (int m = 0; m < 4; ++m)
; #pragma unroll
;                     for (int n = 0; n < 2; ++n) acc[a][b][m][n] = (f32x4){0.f, 0.f, 0.f, 0.f};
;         cur = nxt; cA = nA; cB = nB; ++ui;
.LBB0_968:
	s_ashr_i32 s17, s16, 31
	s_lshl_b64 s[18:19], s[16:17], 19
	s_add_u32 s18, s30, s18
	s_addc_u32 s19, s31, s19
	s_and_b64 s[20:21], s[2:3], exec
	s_cselect_b32 s17, s19, s25
	s_cselect_b32 s51, s18, s24
	s_ashr_i32 s15, s14, 31
	s_lshl_b64 s[20:21], s[14:15], 19
	s_add_u32 s20, s34, s20
	s_addc_u32 s21, s35, s21
	s_and_b64 s[28:29], s[2:3], exec
	s_cselect_b32 s15, s21, s27
	s_cselect_b32 s54, s20, s26
	s_add_u32 s24, s24, 0x40080
	s_addc_u32 s25, s25, 0
	s_add_u32 s55, s26, 0x100
	v_mov_b32_e32 v0, 0
	s_addc_u32 s56, s27, 0
	s_mov_b32 s57, -2
	v_mov_b32_e32 v1, v0
	v_mov_b32_e32 v2, v0
	v_mov_b32_e32 v3, v0
	v_mov_b32_e32 v4, v0
	v_mov_b32_e32 v5, v0
	v_mov_b32_e32 v6, v0
	v_mov_b32_e32 v7, v0
	v_mov_b32_e32 v16, v0
	v_mov_b32_e32 v17, v0
	v_mov_b32_e32 v18, v0
	v_mov_b32_e32 v19, v0
	v_mov_b32_e32 v24, v0
	v_mov_b32_e32 v25, v0
	v_mov_b32_e32 v26, v0
	v_mov_b32_e32 v27, v0
	v_mov_b32_e32 v32, v0
	v_mov_b32_e32 v33, v0
	v_mov_b32_e32 v34, v0
	v_mov_b32_e32 v35, v0
	v_mov_b32_e32 v36, v0
	v_mov_b32_e32 v37, v0
	v_mov_b32_e32 v38, v0
	v_mov_b32_e32 v39, v0
	v_mov_b32_e32 v48, v0
	v_mov_b32_e32 v49, v0
	v_mov_b32_e32 v50, v0
	v_mov_b32_e32 v51, v0
	v_mov_b32_e32 v56, v0
	v_mov_b32_e32 v57, v0
	v_mov_b32_e32 v58, v0
	v_mov_b32_e32 v59, v0
	v_mov_b32_e32 v8, v0
	v_mov_b32_e32 v9, v0
	v_mov_b32_e32 v10, v0
	v_mov_b32_e32 v11, v0
	v_mov_b32_e32 v12, v0
	v_mov_b32_e32 v13, v0
	v_mov_b32_e32 v14, v0
	v_mov_b32_e32 v15, v0
	v_mov_b32_e32 v20, v0
	v_mov_b32_e32 v21, v0
	v_mov_b32_e32 v22, v0
	v_mov_b32_e32 v23, v0
	v_mov_b32_e32 v28, v0
	v_mov_b32_e32 v29, v0
	v_mov_b32_e32 v30, v0
	v_mov_b32_e32 v31, v0
	v_mov_b32_e32 v40, v0
	v_mov_b32_e32 v41, v0
	v_mov_b32_e32 v42, v0
	v_mov_b32_e32 v43, v0
	v_mov_b32_e32 v44, v0
	v_mov_b32_e32 v45, v0
	v_mov_b32_e32 v46, v0
	v_mov_b32_e32 v47, v0
	v_mov_b32_e32 v52, v0
	v_mov_b32_e32 v53, v0
	v_mov_b32_e32 v54, v0
	v_mov_b32_e32 v55, v0
	v_mov_b32_e32 v60, v0
	v_mov_b32_e32 v61, v0
	v_mov_b32_e32 v62, v0
	v_mov_b32_e32 v63, v0
	v_mov_b32_e32 v64, v0
	v_mov_b32_e32 v65, v0
	v_mov_b32_e32 v66, v0
	v_mov_b32_e32 v67, v0
	v_mov_b32_e32 v68, v0
	v_mov_b32_e32 v69, v0
	v_mov_b32_e32 v70, v0
	v_mov_b32_e32 v71, v0
	v_mov_b32_e32 v80, v0
	v_mov_b32_e32 v81, v0
	v_mov_b32_e32 v82, v0
	v_mov_b32_e32 v83, v0
	v_mov_b32_e32 v88, v0
	v_mov_b32_e32 v89, v0
	v_mov_b32_e32 v90, v0
	v_mov_b32_e32 v91, v0
	v_mov_b32_e32 v96, v0
	v_mov_b32_e32 v97, v0
	v_mov_b32_e32 v98, v0
	v_mov_b32_e32 v99, v0
	v_mov_b32_e32 v100, v0
	v_mov_b32_e32 v101, v0
	v_mov_b32_e32 v102, v0
	v_mov_b32_e32 v103, v0
	v_mov_b32_e32 v112, v0
	v_mov_b32_e32 v113, v0
	v_mov_b32_e32 v114, v0
	v_mov_b32_e32 v115, v0
	v_mov_b32_e32 v116, v0
	v_mov_b32_e32 v117, v0
	v_mov_b32_e32 v118, v0
	v_mov_b32_e32 v119, v0
	v_mov_b32_e32 v72, v0
	v_mov_b32_e32 v73, v0
	v_mov_b32_e32 v74, v0
	v_mov_b32_e32 v75, v0
	v_mov_b32_e32 v76, v0
	v_mov_b32_e32 v77, v0
	v_mov_b32_e32 v78, v0
	v_mov_b32_e32 v79, v0
	v_mov_b32_e32 v84, v0
	v_mov_b32_e32 v85, v0
	v_mov_b32_e32 v86, v0
	v_mov_b32_e32 v87, v0
	v_mov_b32_e32 v92, v0
	v_mov_b32_e32 v93, v0
	v_mov_b32_e32 v94, v0
	v_mov_b32_e32 v95, v0
	v_mov_b32_e32 v104, v0
	v_mov_b32_e32 v105, v0
	v_mov_b32_e32 v106, v0
	v_mov_b32_e32 v107, v0
	v_mov_b32_e32 v108, v0
	v_mov_b32_e32 v109, v0
	v_mov_b32_e32 v110, v0
	v_mov_b32_e32 v111, v0
	v_mov_b32_e32 v120, v0
	v_mov_b32_e32 v121, v0
	v_mov_b32_e32 v122, v0
	v_mov_b32_e32 v123, v0
	v_mov_b32_e32 v124, v0
	v_mov_b32_e32 v125, v0
	v_mov_b32_e32 v126, v0
	v_mov_b32_e32 v127, v0
	v_readfirstlane_b32 s100, v188
	s_bitcmp0_b32 s100, 8
	s_cbranch_scc0 .Lmy_sprio_969
	s_setprio 1

; template <class Epi, class Sched, bool ALIGN_EPI = false, bool SP2 = false>
; __device__ __forceinline__ void gemm_phase(PG8_LAS unsigned char* lds, const Gemm g, const Sched& S, const Epi& E) {
;     ...
;         for (int a = 0; a < 2; ++a)
; #pragma unroll
;             for (int b = 0; b < 2; ++b)
; #pragma unroll
;                 for (int m = 0; m < 4; ++m)
; #pragma unroll
;                     for (int n = 0; n < 2; ++n) acc[a][b][m][n] = (f32x4){0.f, 0.f, 0.f, 0.f};
;         cur = nxt; cA = nA; cB = nB; ++ui;
.LBB0_1051:
	s_add_u32 s54, s24, 0x100
	v_mov_b32_e32 v0, 0
	s_addc_u32 s55, s25, 0
	s_mov_b32 s56, -2
	v_mov_b32_e32 v1, v0
	v_mov_b32_e32 v2, v0
	v_mov_b32_e32 v3, v0
	v_mov_b32_e32 v4, v0
	v_mov_b32_e32 v5, v0
	v_mov_b32_e32 v6, v0
	v_mov_b32_e32 v7, v0
	v_mov_b32_e32 v16, v0
	v_mov_b32_e32 v17, v0
	v_mov_b32_e32 v18, v0
	v_mov_b32_e32 v19, v0
	v_mov_b32_e32 v20, v0
	v_mov_b32_e32 v21, v0
	v_mov_b32_e32 v22, v0
	v_mov_b32_e32 v23, v0
	v_mov_b32_e32 v32, v0
	v_mov_b32_e32 v33, v0
	v_mov_b32_e32 v34, v0
	v_mov_b32_e32 v35, v0
	v_mov_b32_e32 v36, v0
	v_mov_b32_e32 v37, v0
	v_mov_b32_e32 v38, v0
	v_mov_b32_e32 v39, v0
	v_mov_b32_e32 v48, v0
	v_mov_b32_e32 v49, v0
	v_mov_b32_e32 v50, v0
	v_mov_b32_e32 v51, v0
	v_mov_b32_e32 v52, v0
	v_mov_b32_e32 v53, v0
	v_mov_b32_e32 v54, v0
	v_mov_b32_e32 v55, v0
	v_mov_b32_e32 v8, v0
	v_mov_b32_e32 v9, v0
	v_mov_b32_e32 v10, v0
	v_mov_b32_e32 v11, v0
	v_mov_b32_e32 v12, v0
	v_mov_b32_e32 v13, v0
	v_mov_b32_e32 v14, v0
	v_mov_b32_e32 v15, v0
	v_mov_b32_e32 v24, v0
	v_mov_b32_e32 v25, v0
	v_mov_b32_e32 v26, v0
	v_mov_b32_e32 v27, v0
	v_mov_b32_e32 v28, v0
	v_mov_b32_e32 v29, v0
	v_mov_b32_e32 v30, v0
	v_mov_b32_e32 v31, v0
	v_mov_b32_e32 v40, v0
	v_mov_b32_e32 v41, v0
	v_mov_b32_e32 v42, v0
	v_mov_b32_e32 v43, v0
	v_mov_b32_e32 v44, v0
	v_mov_b32_e32 v45, v0
	v_mov_b32_e32 v46, v0
	v_mov_b32_e32 v47, v0
	v_mov_b32_e32 v56, v0
	v_mov_b32_e32 v57, v0
	v_mov_b32_e32 v58, v0
	v_mov_b32_e32 v59, v0
	v_mov_b32_e32 v60, v0
	v_mov_b32_e32 v61, v0
	v_mov_b32_e32 v62, v0
	v_mov_b32_e32 v63, v0
	v_mov_b32_e32 v64, v0
	v_mov_b32_e32 v65, v0
	v_mov_b32_e32 v66, v0
	v_mov_b32_e32 v67, v0
	v_mov_b32_e32 v68, v0
	v_mov_b32_e32 v69, v0
	v_mov_b32_e32 v70, v0
	v_mov_b32_e32 v71, v0
	v_mov_b32_e32 v80, v0
	v_mov_b32_e32 v81, v0
	v_mov_b32_e32 v82, v0
	v_mov_b32_e32 v83, v0
	v_mov_b32_e32 v84, v0
	v_mov_b32_e32 v85, v0
	v_mov_b32_e32 v86, v0
	v_mov_b32_e32 v87, v0
	v_mov_b32_e32 v96, v0
	v_mov_b32_e32 v97, v0
	v_mov_b32_e32 v98, v0
	v_mov_b32_e32 v99, v0
	v_mov_b32_e32 v100, v0
	v_mov_b32_e32 v101, v0
	v_mov_b32_e32 v102, v0
	v_mov_b32_e32 v103, v0
	v_mov_b32_e32 v104, v0
	v_mov_b32_e32 v105, v0
	v_mov_b32_e32 v106, v0
	v_mov_b32_e32 v107, v0
	v_mov_b32_e32 v108, v0
	v_mov_b32_e32 v109, v0
	v_mov_b32_e32 v110, v0
	v_mov_b32_e32 v111, v0
	v_mov_b32_e32 v72, v0
	v_mov_b32_e32 v73, v0
	v_mov_b32_e32 v74, v0
	v_mov_b32_e32 v75, v0
	v_mov_b32_e32 v76, v0
	v_mov_b32_e32 v77, v0
	v_mov_b32_e32 v78, v0
	v_mov_b32_e32 v79, v0
	v_mov_b32_e32 v88, v0
	v_mov_b32_e32 v89, v0
	v_mov_b32_e32 v90, v0
	v_mov_b32_e32 v91, v0
	v_mov_b32_e32 v92, v0
	v_mov_b32_e32 v93, v0
	v_mov_b32_e32 v94, v0
	v_mov_b32_e32 v95, v0
	v_mov_b32_e32 v112, v0
	v_mov_b32_e32 v113, v0
	v_mov_b32_e32 v114, v0
	v_mov_b32_e32 v115, v0
	v_mov_b32_e32 v116, v0
	v_mov_b32_e32 v117, v0
	v_mov_b32_e32 v118, v0
	v_mov_b32_e32 v119, v0
	v_mov_b32_e32 v120, v0
	v_mov_b32_e32 v121, v0
	v_mov_b32_e32 v122, v0
	v_mov_b32_e32 v123, v0
	v_mov_b32_e32 v124, v0
	v_mov_b32_e32 v125, v0
	v_mov_b32_e32 v126, v0
	v_mov_b32_e32 v127, v0
	v_readfirstlane_b32 s100, v188
	s_bitcmp0_b32 s100, 8
	s_cbranch_scc0 .Lmy_sprio_1052
	s_setprio 1
